# P5 scan/attention order split by workgroup bit 3 (mixes both orders inside every XCD) instead of bit 0
# baseline (speedup 1.0000x reference)
.LBB0_670:
	v_writelane_b32 v255, s64, 53
	s_cmpk_gt_i32 s16, 0xff
	v_mbcnt_lo_u32_b32 v0, -1, 0
	v_mbcnt_hi_u32_b32 v0, -1, v0
	s_cbranch_scc1 .LBB0_711
	s_bitcmp1_b32 s64, 3
	s_cbranch_scc0 .Lp5_attn_entry
	s_cmp_eq_u32 s98, 0x52
	s_cbranch_scc1 .Lp5_attn_entry
	s_mov_b32 s98, 0x51
	s_mov_b32 s99, s16
	v_readlane_b32 s73, v254, 20
	s_branch .LBB0_711
